# Fourier item readout: mirror piece as one 16-byte store of the rotated vector (fk >= 1) instead of three partial stores
# speedup vs baseline: 1.0038x; 1.0038x over previous
.LBB0_481:
	s_add_u32 s2, s2, 0xb200000
	v_add_u32_e32 v6, s91, v130
	s_addc_u32 s3, s3, 0
	s_mov_b64 s[12:13], -1
	s_and_b64 vcc, exec, s[4:5]
	v_ashrrev_i32_e32 v7, 31, v6
	v_lshl_add_u32 v10, v6, 4, 0
	s_waitcnt lgkmcnt(0)
	s_barrier
	s_cbranch_vccnz .LBB0_499
	s_lshl_b32 s4, s61, 23
	s_add_u32 s4, s2, s4
	s_addc_u32 s5, s3, 0
	s_lshl_b32 s12, s68, 1
	s_add_u32 s74, s4, s12
	s_addc_u32 s75, s5, 0
	s_lshl_b32 s4, s60, 1
	ds_read_b128 v[12:15], v10
	v_add_u32_e32 v0, 0x10000, v10
	s_add_u32 s76, s74, s4
	ds_read_b128 v[2:5], v0
	s_mov_b32 s5, 0x3ffc00
	s_addc_u32 s77, s75, 0
	v_mul_lo_u32 v11, v6, s5
	s_cmp_lg_u32 s57, 0
	v_lshlrev_b64 v[8:9], 11, v[6:7]
	v_and_b32_e32 v0, 0x3ffc00, v11
	s_cselect_b64 s[12:13], -1, 0
	s_xor_b32 s46, s60, 56
	v_lshl_add_u64 v[8:9], s[76:77], 0, v[8:9]
	v_lshlrev_b32_e32 v0, 1, v0
	s_sub_i32 s61, 0x80, s60
	s_lshl_b32 s4, s46, 1
	s_waitcnt lgkmcnt(1)
	global_store_dwordx4 v[8:9], v[12:15], off offset:1024
	v_lshl_add_u64 v[8:9], s[74:75], 0, v[0:1]
	s_mov_b32 s5, s47
	s_cmp_eq_u32 s57, 0
	v_lshl_add_u64 v[16:17], v[8:9], 0, s[4:5]
	s_waitcnt lgkmcnt(0)
	v_mov_b32_e32 v12, v3
	v_mov_b32_e32 v13, v4
	v_mov_b32_e32 v14, v5
	s_cbranch_scc1 .Lfft_fk0_1
	v_alignbit_b32 v12, v3, v2, 16
	v_alignbit_b32 v13, v4, v3, 16
	v_alignbit_b32 v14, v5, v4, 16
	v_alignbit_b32 v15, v2, v5, 16
	global_store_dwordx4 v[16:17], v[12:15], off offset:1154
	s_branch .LBB0_484
.Lfft_fk0_1:
	global_store_short_d16_hi v[16:17], v2, off offset:1154
	global_store_dwordx3 v[16:17], v[12:14], off offset:1156
.LBB0_484:
	v_add_u32_e32 v8, 0x200, v6
	v_lshl_add_u32 v0, v8, 4, 0
	v_add_u32_e32 v2, 0x10000, v0
	ds_read_b128 v[12:15], v0
	ds_read_b128 v[2:5], v2
	v_ashrrev_i32_e32 v9, 31, v8
	v_add_u32_e32 v11, 0x7ff80000, v11
	v_lshlrev_b64 v[8:9], 11, v[8:9]
	v_and_b32_e32 v0, 0x3ffc00, v11
	v_lshl_add_u64 v[8:9], s[76:77], 0, v[8:9]
	v_lshlrev_b32_e32 v0, 1, v0
	s_waitcnt lgkmcnt(1)
	global_store_dwordx4 v[8:9], v[12:15], off offset:1024
	v_lshl_add_u64 v[8:9], s[74:75], 0, v[0:1]
	v_cndmask_b32_e64 v0, 0, 1, s[12:13]
	v_lshl_add_u64 v[16:17], s[46:47], 1, v[8:9]
	s_waitcnt lgkmcnt(0)
	v_mov_b32_e32 v12, v3
	v_mov_b32_e32 v13, v4
	v_mov_b32_e32 v14, v5
	v_cmp_ne_u32_e64 s[4:5], 1, v0
	s_andn2_b64 vcc, exec, s[12:13]
	s_cbranch_vccnz .Lfft_fk0_2
	v_alignbit_b32 v12, v3, v2, 16
	v_alignbit_b32 v13, v4, v3, 16
	v_alignbit_b32 v14, v5, v4, 16
	v_alignbit_b32 v15, v2, v5, 16
	global_store_dwordx4 v[16:17], v[12:15], off offset:1154
	s_branch .LBB0_486

.LBB0_486:
	v_add_u32_e32 v8, 0x400, v6
	v_lshl_add_u32 v0, v8, 4, 0
	v_add_u32_e32 v2, 0x10000, v0
	ds_read_b128 v[12:15], v0
	ds_read_b128 v[2:5], v2
	v_ashrrev_i32_e32 v9, 31, v8
	v_add_u32_e32 v11, 0x7ff80000, v11
	v_lshlrev_b64 v[8:9], 11, v[8:9]
	v_and_b32_e32 v0, 0x3ffc00, v11
	v_lshl_add_u64 v[8:9], s[76:77], 0, v[8:9]
	v_lshlrev_b32_e32 v0, 1, v0
	s_waitcnt lgkmcnt(1)
	global_store_dwordx4 v[8:9], v[12:15], off offset:1024
	v_lshl_add_u64 v[8:9], s[74:75], 0, v[0:1]
	v_lshl_add_u64 v[16:17], s[46:47], 1, v[8:9]
	s_waitcnt lgkmcnt(0)
	v_mov_b32_e32 v12, v3
	v_mov_b32_e32 v13, v4
	v_mov_b32_e32 v14, v5
	s_and_b64 vcc, exec, s[4:5]
	s_cbranch_vccnz .Lfft_fk0_3
	v_alignbit_b32 v12, v3, v2, 16
	v_alignbit_b32 v13, v4, v3, 16
	v_alignbit_b32 v14, v5, v4, 16
	v_alignbit_b32 v15, v2, v5, 16
	global_store_dwordx4 v[16:17], v[12:15], off offset:1154
	s_branch .LBB0_488

.LBB0_488:
	v_add_u32_e32 v8, 0x600, v6
	v_lshl_add_u32 v0, v8, 4, 0
	v_add_u32_e32 v2, 0x10000, v0
	ds_read_b128 v[12:15], v0
	ds_read_b128 v[2:5], v2
	v_ashrrev_i32_e32 v9, 31, v8
	v_add_u32_e32 v11, 0x7ff80000, v11
	v_lshlrev_b64 v[8:9], 11, v[8:9]
	v_and_b32_e32 v0, 0x3ffc00, v11
	v_lshl_add_u64 v[8:9], s[76:77], 0, v[8:9]
	v_lshlrev_b32_e32 v0, 1, v0
	s_waitcnt lgkmcnt(1)
	global_store_dwordx4 v[8:9], v[12:15], off offset:1024
	v_lshl_add_u64 v[8:9], s[74:75], 0, v[0:1]
	v_lshl_add_u64 v[16:17], s[46:47], 1, v[8:9]
	s_waitcnt lgkmcnt(0)
	v_mov_b32_e32 v12, v3
	v_mov_b32_e32 v13, v4
	v_mov_b32_e32 v14, v5
	s_and_b64 vcc, exec, s[4:5]
	s_cbranch_vccnz .Lfft_fk0_4
	v_alignbit_b32 v12, v3, v2, 16
	v_alignbit_b32 v13, v4, v3, 16
	v_alignbit_b32 v14, v5, v4, 16
	v_alignbit_b32 v15, v2, v5, 16
	global_store_dwordx4 v[16:17], v[12:15], off offset:1154
	s_branch .LBB0_490

.LBB0_490:
	v_add_u32_e32 v8, 0x800, v6
	v_lshl_add_u32 v0, v8, 4, 0
	v_add_u32_e32 v2, 0x10000, v0
	ds_read_b128 v[12:15], v0
	ds_read_b128 v[2:5], v2
	v_ashrrev_i32_e32 v9, 31, v8
	v_add_u32_e32 v11, 0x7ff80000, v11
	v_lshlrev_b64 v[8:9], 11, v[8:9]
	v_and_b32_e32 v0, 0x3ffc00, v11
	v_lshl_add_u64 v[8:9], s[76:77], 0, v[8:9]
	v_lshlrev_b32_e32 v0, 1, v0
	s_waitcnt lgkmcnt(1)
	global_store_dwordx4 v[8:9], v[12:15], off offset:1024
	v_lshl_add_u64 v[8:9], s[74:75], 0, v[0:1]
	v_lshl_add_u64 v[16:17], s[46:47], 1, v[8:9]
	s_waitcnt lgkmcnt(0)
	v_mov_b32_e32 v12, v3
	v_mov_b32_e32 v13, v4
	v_mov_b32_e32 v14, v5
	s_and_b64 vcc, exec, s[4:5]
	s_cbranch_vccnz .Lfft_fk0_5
	v_alignbit_b32 v12, v3, v2, 16
	v_alignbit_b32 v13, v4, v3, 16
	v_alignbit_b32 v14, v5, v4, 16
	v_alignbit_b32 v15, v2, v5, 16
	global_store_dwordx4 v[16:17], v[12:15], off offset:1154
	s_branch .LBB0_492

.LBB0_492:
	v_add_u32_e32 v8, 0xa00, v6
	v_lshl_add_u32 v0, v8, 4, 0
	v_add_u32_e32 v2, 0x10000, v0
	ds_read_b128 v[12:15], v0
	ds_read_b128 v[2:5], v2
	v_ashrrev_i32_e32 v9, 31, v8
	v_add_u32_e32 v11, 0x7ff80000, v11
	v_lshlrev_b64 v[8:9], 11, v[8:9]
	v_and_b32_e32 v0, 0x3ffc00, v11
	v_lshl_add_u64 v[8:9], s[76:77], 0, v[8:9]
	v_lshlrev_b32_e32 v0, 1, v0
	s_waitcnt lgkmcnt(1)
	global_store_dwordx4 v[8:9], v[12:15], off offset:1024
	v_lshl_add_u64 v[8:9], s[74:75], 0, v[0:1]
	v_lshl_add_u64 v[16:17], s[46:47], 1, v[8:9]
	s_waitcnt lgkmcnt(0)
	v_mov_b32_e32 v12, v3
	v_mov_b32_e32 v13, v4
	v_mov_b32_e32 v14, v5
	s_and_b64 vcc, exec, s[4:5]
	s_cbranch_vccnz .Lfft_fk0_6
	v_alignbit_b32 v12, v3, v2, 16
	v_alignbit_b32 v13, v4, v3, 16
	v_alignbit_b32 v14, v5, v4, 16
	v_alignbit_b32 v15, v2, v5, 16
	global_store_dwordx4 v[16:17], v[12:15], off offset:1154
	s_branch .LBB0_494

.LBB0_494:
	v_add_u32_e32 v8, 0xc00, v6
	v_lshl_add_u32 v0, v8, 4, 0
	v_add_u32_e32 v2, 0x10000, v0
	ds_read_b128 v[12:15], v0
	ds_read_b128 v[2:5], v2
	v_ashrrev_i32_e32 v9, 31, v8
	v_add_u32_e32 v11, 0x7ff80000, v11
	v_lshlrev_b64 v[8:9], 11, v[8:9]
	v_and_b32_e32 v0, 0x3ffc00, v11
	v_lshl_add_u64 v[8:9], s[76:77], 0, v[8:9]
	v_lshlrev_b32_e32 v0, 1, v0
	s_waitcnt lgkmcnt(1)
	global_store_dwordx4 v[8:9], v[12:15], off offset:1024
	v_lshl_add_u64 v[8:9], s[74:75], 0, v[0:1]
	v_lshl_add_u64 v[16:17], s[46:47], 1, v[8:9]
	s_waitcnt lgkmcnt(0)
	v_mov_b32_e32 v12, v3
	v_mov_b32_e32 v13, v4
	v_mov_b32_e32 v14, v5
	s_and_b64 vcc, exec, s[4:5]
	s_cbranch_vccnz .Lfft_fk0_7
	v_alignbit_b32 v12, v3, v2, 16
	v_alignbit_b32 v13, v4, v3, 16
	v_alignbit_b32 v14, v5, v4, 16
	v_alignbit_b32 v15, v2, v5, 16
	global_store_dwordx4 v[16:17], v[12:15], off offset:1154
	s_branch .LBB0_496

.LBB0_496:
	v_add_u32_e32 v8, 0xe00, v6
	v_lshl_add_u32 v0, v8, 4, 0
	v_add_u32_e32 v2, 0x10000, v0
	ds_read_b128 v[12:15], v0
	ds_read_b128 v[2:5], v2
	v_ashrrev_i32_e32 v9, 31, v8
	v_add_u32_e32 v0, 0x7ff80000, v11
	v_lshlrev_b64 v[8:9], 11, v[8:9]
	v_and_b32_e32 v0, 0x3ffc00, v0
	v_lshl_add_u64 v[8:9], s[76:77], 0, v[8:9]
	v_lshlrev_b32_e32 v0, 1, v0
	s_waitcnt lgkmcnt(1)
	global_store_dwordx4 v[8:9], v[12:15], off offset:1024
	v_lshl_add_u64 v[8:9], s[74:75], 0, v[0:1]
	v_lshl_add_u64 v[16:17], s[46:47], 1, v[8:9]
	s_waitcnt lgkmcnt(0)
	v_mov_b32_e32 v12, v3
	v_mov_b32_e32 v13, v4
	v_mov_b32_e32 v14, v5
	s_and_b64 vcc, exec, s[4:5]
	s_cbranch_vccnz .Lfft_fk0_8
	v_alignbit_b32 v12, v3, v2, 16
	v_alignbit_b32 v13, v4, v3, 16
	v_alignbit_b32 v14, v5, v4, 16
	v_alignbit_b32 v15, v2, v5, 16
	global_store_dwordx4 v[16:17], v[12:15], off offset:1154
	s_branch .LBB0_498
